# plus P5: residual tile (128 KiB of bf16 x per workgroup) requested at phase start into v255 so the epilogue reads it from cache
# baseline (speedup 1.0000x reference)
.LBB0_2455:
	s_cmp_gt_i32 s28, 5
	s_cselect_b64 s[0:1], -1, 0
	s_cmp_lt_i32 s29, 6
	s_cselect_b64 s[2:3], -1, 0
	s_or_b64 s[0:1], s[0:1], s[2:3]
	s_and_b64 vcc, exec, s[0:1]
	s_cbranch_vccnz .LBB0_2538
	s_add_u32 s24, s26, 0x12400000
	s_addc_u32 s25, s27, 0
	s_add_u32 s22, s26, 0x2a00000
	s_addc_u32 s23, s27, 0
	s_add_u32 s4, s26, 0x7400000
	s_addc_u32 s5, s27, 0
	s_and_b32 s0, s89, 7
	s_lshl_b32 s0, s0, 2
	s_lshr_b32 s1, s89, 6
	s_add_i32 s0, s0, s1
	s_lshl_b32 s0, s0, 20
	s_lshr_b32 s1, s89, 3
	s_and_b32 s1, s1, 7
	s_lshl_b32 s1, s1, 9
	s_add_i32 s0, s0, s1
	v_lshrrev_b32_e32 v1, 2, v0
	v_lshlrev_b32_e32 v1, 12, v1
	v_and_b32_e32 v2, 3, v0
	v_lshl_add_u32 v1, v2, 7, v1
	v_add_u32_e32 v1, s0, v1
	global_load_dword v255, v1, s[4:5]
	v_add_u32_e32 v2, 0x80000, v1
	global_load_dword v255, v2, s[4:5]
	s_add_u32 s2, s26, 0x14600000
	s_addc_u32 s3, s27, 0
	s_bitcmp0_b32 s89, 0
	v_readlane_b32 s0, v251, 0
	s_cselect_b64 s[6:7], -1, 0
	s_bitcmp1_b32 s0, 1
	s_cselect_b64 s[0:1], -1, 0
	s_or_b64 s[0:1], s[6:7], s[0:1]
	s_mov_b32 s9, 0
	s_and_b64 vcc, exec, s[0:1]
	s_cbranch_vccnz .LBB0_2460
	s_lshl_b32 s0, s89, 1
	s_andn2_b32 s0, s0, 63
	s_addk_i32 s0, 0x2000
	s_ashr_i32 s1, s0, 31
	s_and_b32 s10, s89, 31
	s_lshl_b64 s[12:13], s[0:1], 12
	s_add_u32 s12, s24, s12
	s_addc_u32 s13, s25, s13
	s_lshl_b32 s1, s10, 18
	v_and_b32_e32 v1, 15, v0
	s_add_u32 s14, s22, s1
	s_waitcnt vmcnt(0)
	v_lshlrev_b32_e32 v2, 12, v1
	v_mov_b32_e32 v3, 0
	s_addc_u32 s15, s23, 0
	s_lshl_b32 s8, s88, 9
	v_lshl_add_u64 v[8:9], s[12:13], 0, v[2:3]
	v_lshl_add_u64 v[4:5], s[14:15], 0, v[2:3]
	v_and_b32_e32 v2, 48, v0
	v_lshl_add_u64 v[8:9], v[8:9], 0, s[8:9]
	v_lshl_add_u64 v[208:209], v[8:9], 0, v[2:3]
	s_mov_b32 s1, 0x10000
	v_add_co_u32_e32 v210, vcc, s1, v208
	v_lshl_add_u64 v[4:5], v[4:5], 0, s[8:9]
	s_mov_b32 s8, 0x20000
	v_addc_co_u32_e32 v211, vcc, 0, v209, vcc
	v_add_co_u32_e32 v212, vcc, s8, v208
	s_mov_b32 s9, 0x30000
	s_nop 0
	v_addc_co_u32_e32 v213, vcc, 0, v209, vcc
	v_add_co_u32_e32 v214, vcc, s9, v208
	v_lshl_add_u64 v[196:197], v[4:5], 0, v[2:3]
	s_nop 0
	v_addc_co_u32_e32 v215, vcc, 0, v209, vcc
	v_add_co_u32_e32 v216, vcc, s1, v196
	global_load_dwordx4 v[4:7], v[196:197], off
	global_load_dwordx4 v[8:11], v[208:209], off
	v_addc_co_u32_e32 v217, vcc, 0, v197, vcc
	v_add_co_u32_e32 v218, vcc, s8, v196
	global_load_dwordx4 v[12:15], v[210:211], off
	global_load_dwordx4 v[16:19], v[212:213], off
	v_addc_co_u32_e32 v219, vcc, 0, v197, vcc
	v_add_co_u32_e32 v220, vcc, s9, v196
	global_load_dwordx4 v[20:23], v[208:209], off offset:64
	global_load_dwordx4 v[24:27], v[208:209], off offset:256
	v_addc_co_u32_e32 v221, vcc, 0, v197, vcc
	global_load_dwordx4 v[32:35], v[214:215], off
	global_load_dwordx4 v[36:39], v[210:211], off offset:64
	global_load_dwordx4 v[44:47], v[212:213], off offset:64
	global_load_dwordx4 v[48:51], v[216:217], off
	global_load_dwordx4 v[56:59], v[214:215], off offset:64
	global_load_dwordx4 v[60:63], v[218:219], off
	global_load_dwordx4 v[64:67], v[210:211], off offset:256
	global_load_dwordx4 v[72:75], v[212:213], off offset:256
	global_load_dwordx4 v[80:83], v[220:221], off
	global_load_dwordx4 v[84:87], v[214:215], off offset:256
	global_load_dwordx4 v[96:99], v[208:209], off offset:128
	global_load_dwordx4 v[100:103], v[208:209], off offset:192
	global_load_dwordx4 v[108:111], v[196:197], off offset:64
	global_load_dwordx4 v[112:115], v[196:197], off offset:128
	global_load_dwordx4 v[116:119], v[210:211], off offset:128
	global_load_dwordx4 v[120:123], v[210:211], off offset:192
	global_load_dwordx4 v[128:131], v[212:213], off offset:128
	global_load_dwordx4 v[132:135], v[212:213], off offset:192
	global_load_dwordx4 v[136:139], v[214:215], off offset:128
	global_load_dwordx4 v[140:143], v[214:215], off offset:192
	global_load_dwordx4 v[144:147], v[196:197], off offset:192
	global_load_dwordx4 v[148:151], v[196:197], off offset:256
	global_load_dwordx4 v[152:155], v[216:217], off offset:64
	global_load_dwordx4 v[156:159], v[216:217], off offset:128
	s_waitcnt lgkmcnt(0)
	global_load_dwordx4 v[160:163], v[218:219], off offset:64
	global_load_dwordx4 v[164:167], v[218:219], off offset:128
	global_load_dwordx4 v[168:171], v[220:221], off offset:64
	global_load_dwordx4 v[172:175], v[220:221], off offset:128
	global_load_dwordx4 v[176:179], v[216:217], off offset:192
	global_load_dwordx4 v[180:183], v[216:217], off offset:256
	global_load_dwordx4 v[184:187], v[218:219], off offset:192
	global_load_dwordx4 v[188:191], v[218:219], off offset:256
	global_load_dwordx4 v[192:195], v[220:221], off offset:192
	global_load_dwordx4 v[200:203], v[220:221], off offset:256
	s_waitcnt vmcnt(38)
	v_mfma_f32_16x16x32_bf16 v[28:31], v[4:7], v[8:11], 0
	s_waitcnt vmcnt(37)
	v_mfma_f32_16x16x32_bf16 v[40:43], v[4:7], v[12:15], 0
	s_waitcnt vmcnt(36)
	v_mfma_f32_16x16x32_bf16 v[52:55], v[4:7], v[16:19], 0
	s_waitcnt vmcnt(33)
	v_mfma_f32_16x16x32_bf16 v[4:7], v[4:7], v[32:35], 0
	s_waitcnt vmcnt(30)
	v_mfma_f32_16x16x32_bf16 v[68:71], v[48:51], v[8:11], 0
	s_waitcnt vmcnt(28)
	v_mfma_f32_16x16x32_bf16 v[76:79], v[60:63], v[8:11], 0
	s_waitcnt vmcnt(25)
	v_mfma_f32_16x16x32_bf16 v[8:11], v[80:83], v[8:11], 0
	v_mfma_f32_16x16x32_bf16 v[88:91], v[48:51], v[12:15], 0
	v_mfma_f32_16x16x32_bf16 v[92:95], v[60:63], v[12:15], 0
	v_mfma_f32_16x16x32_bf16 v[12:15], v[80:83], v[12:15], 0
	v_mfma_f32_16x16x32_bf16 v[104:107], v[48:51], v[16:19], 0
	v_mfma_f32_16x16x32_bf16 v[124:127], v[60:63], v[16:19], 0
	v_mfma_f32_16x16x32_bf16 v[16:19], v[80:83], v[16:19], 0
	v_mfma_f32_16x16x32_bf16 v[48:51], v[48:51], v[32:35], 0
	v_mfma_f32_16x16x32_bf16 v[60:63], v[60:63], v[32:35], 0
	v_mfma_f32_16x16x32_bf16 v[32:35], v[80:83], v[32:35], 0
	s_waitcnt vmcnt(21)
	v_mfma_f32_16x16x32_bf16 v[28:31], v[108:111], v[20:23], v[28:31]
	s_waitcnt vmcnt(11)
	v_mfma_f32_16x16x32_bf16 v[68:71], v[152:155], v[20:23], v[68:71]
	s_waitcnt vmcnt(9)
	v_mfma_f32_16x16x32_bf16 v[76:79], v[160:163], v[20:23], v[76:79]
	s_waitcnt vmcnt(7)
	v_mfma_f32_16x16x32_bf16 v[8:11], v[168:171], v[20:23], v[8:11]
	v_mfma_f32_16x16x32_bf16 v[20:23], v[108:111], v[36:39], v[40:43]
	v_mfma_f32_16x16x32_bf16 v[40:43], v[152:155], v[36:39], v[88:91]
	v_mfma_f32_16x16x32_bf16 v[80:83], v[160:163], v[36:39], v[92:95]
	v_mfma_f32_16x16x32_bf16 v[12:15], v[168:171], v[36:39], v[12:15]
	v_mfma_f32_16x16x32_bf16 v[36:39], v[108:111], v[44:47], v[52:55]
	v_mfma_f32_16x16x32_bf16 v[52:55], v[152:155], v[44:47], v[104:107]
	v_mfma_f32_16x16x32_bf16 v[88:91], v[160:163], v[44:47], v[124:127]
	v_mfma_f32_16x16x32_bf16 v[16:19], v[168:171], v[44:47], v[16:19]
	v_mfma_f32_16x16x32_bf16 v[4:7], v[108:111], v[56:59], v[4:7]
	v_mfma_f32_16x16x32_bf16 v[44:47], v[152:155], v[56:59], v[48:51]
	s_nop 2
	global_load_dwordx4 v[48:51], v[208:209], off offset:320
	global_load_dwordx4 v[92:95], v[196:197], off offset:320
	global_load_dwordx4 v[104:107], v[210:211], off offset:320
	global_load_dwordx4 v[108:111], v[216:217], off offset:320
	v_mfma_f32_16x16x32_bf16 v[60:63], v[160:163], v[56:59], v[60:63]
	global_load_dwordx4 v[124:127], v[212:213], off offset:320
	global_load_dwordx4 v[152:155], v[218:219], off offset:320
	global_load_dwordx4 v[160:163], v[214:215], off offset:320
	global_load_dwordx4 v[204:207], v[220:221], off offset:320
	v_mfma_f32_16x16x32_bf16 v[32:35], v[168:171], v[56:59], v[32:35]
	v_mfma_f32_16x16x32_bf16 v[28:31], v[112:115], v[96:99], v[28:31]
	v_mfma_f32_16x16x32_bf16 v[56:59], v[156:159], v[96:99], v[68:71]
	v_mfma_f32_16x16x32_bf16 v[68:71], v[164:167], v[96:99], v[76:79]
	s_waitcnt vmcnt(14)
	v_mfma_f32_16x16x32_bf16 v[8:11], v[172:175], v[96:99], v[8:11]
	v_mfma_f32_16x16x32_bf16 v[20:23], v[112:115], v[116:119], v[20:23]
	v_mfma_f32_16x16x32_bf16 v[40:43], v[156:159], v[116:119], v[40:43]
	v_mfma_f32_16x16x32_bf16 v[76:79], v[164:167], v[116:119], v[80:83]
	v_mfma_f32_16x16x32_bf16 v[12:15], v[172:175], v[116:119], v[12:15]
	v_mfma_f32_16x16x32_bf16 v[36:39], v[112:115], v[128:131], v[36:39]
	v_mfma_f32_16x16x32_bf16 v[52:55], v[156:159], v[128:131], v[52:55]
	v_mfma_f32_16x16x32_bf16 v[80:83], v[164:167], v[128:131], v[88:91]
	v_mfma_f32_16x16x32_bf16 v[16:19], v[172:175], v[128:131], v[16:19]
	v_mfma_f32_16x16x32_bf16 v[4:7], v[112:115], v[136:139], v[4:7]
	s_nop 0
	global_load_dwordx4 v[88:91], v[208:209], off offset:384
	global_load_dwordx4 v[96:99], v[196:197], off offset:384
	global_load_dwordx4 v[112:115], v[210:211], off offset:384
	global_load_dwordx4 v[116:119], v[216:217], off offset:384
	v_mfma_f32_16x16x32_bf16 v[44:47], v[156:159], v[136:139], v[44:47]
	v_mfma_f32_16x16x32_bf16 v[60:63], v[164:167], v[136:139], v[60:63]
	global_load_dwordx4 v[128:131], v[212:213], off offset:384
	global_load_dwordx4 v[156:159], v[218:219], off offset:384
	global_load_dwordx4 v[164:167], v[214:215], off offset:384
	global_load_dwordx4 v[168:171], v[220:221], off offset:384
	v_mfma_f32_16x16x32_bf16 v[32:35], v[172:175], v[136:139], v[32:35]
	v_mfma_f32_16x16x32_bf16 v[28:31], v[144:147], v[100:103], v[28:31]
	s_waitcnt vmcnt(21)
	v_mfma_f32_16x16x32_bf16 v[56:59], v[176:179], v[100:103], v[56:59]
	s_waitcnt vmcnt(19)
	v_mfma_f32_16x16x32_bf16 v[68:71], v[184:187], v[100:103], v[68:71]
	s_waitcnt vmcnt(17)
	v_mfma_f32_16x16x32_bf16 v[8:11], v[192:195], v[100:103], v[8:11]
	v_mfma_f32_16x16x32_bf16 v[20:23], v[144:147], v[120:123], v[20:23]
	v_mfma_f32_16x16x32_bf16 v[40:43], v[176:179], v[120:123], v[40:43]
	v_mfma_f32_16x16x32_bf16 v[76:79], v[184:187], v[120:123], v[76:79]
	v_mfma_f32_16x16x32_bf16 v[12:15], v[192:195], v[120:123], v[12:15]
	v_mfma_f32_16x16x32_bf16 v[36:39], v[144:147], v[132:135], v[36:39]
	v_mfma_f32_16x16x32_bf16 v[52:55], v[176:179], v[132:135], v[52:55]
	v_mfma_f32_16x16x32_bf16 v[80:83], v[184:187], v[132:135], v[80:83]
	v_mfma_f32_16x16x32_bf16 v[16:19], v[192:195], v[132:135], v[16:19]
	global_load_dwordx4 v[100:103], v[208:209], off offset:448
	global_load_dwordx4 v[120:123], v[196:197], off offset:448
	global_load_dwordx4 v[132:135], v[210:211], off offset:448
	global_load_dwordx4 v[136:139], v[216:217], off offset:448
	v_mfma_f32_16x16x32_bf16 v[4:7], v[144:147], v[140:143], v[4:7]
	v_mfma_f32_16x16x32_bf16 v[44:47], v[176:179], v[140:143], v[44:47]
	v_mfma_f32_16x16x32_bf16 v[60:63], v[184:187], v[140:143], v[60:63]
	global_load_dwordx4 v[144:147], v[212:213], off offset:448
	global_load_dwordx4 v[172:175], v[218:219], off offset:448
	global_load_dwordx4 v[176:179], v[214:215], off offset:448
	global_load_dwordx4 v[184:187], v[220:221], off offset:448
	v_mfma_f32_16x16x32_bf16 v[32:35], v[192:195], v[140:143], v[32:35]
	v_mfma_f32_16x16x32_bf16 v[4:7], v[148:151], v[84:87], v[4:7]
	v_mfma_f32_16x16x32_bf16 v[28:31], v[148:151], v[24:27], v[28:31]
	v_mfma_f32_16x16x32_bf16 v[56:59], v[180:183], v[24:27], v[56:59]
	v_mfma_f32_16x16x32_bf16 v[68:71], v[188:191], v[24:27], v[68:71]
	s_waitcnt vmcnt(24)
	v_mfma_f32_16x16x32_bf16 v[8:11], v[200:203], v[24:27], v[8:11]
	v_mfma_f32_16x16x32_bf16 v[20:23], v[148:151], v[64:67], v[20:23]
	v_mfma_f32_16x16x32_bf16 v[24:27], v[180:183], v[64:67], v[40:43]
	v_mfma_f32_16x16x32_bf16 v[40:43], v[188:191], v[64:67], v[76:79]
	v_mfma_f32_16x16x32_bf16 v[12:15], v[200:203], v[64:67], v[12:15]
	v_mfma_f32_16x16x32_bf16 v[36:39], v[148:151], v[72:75], v[36:39]
	v_mfma_f32_16x16x32_bf16 v[52:55], v[180:183], v[72:75], v[52:55]
	v_mfma_f32_16x16x32_bf16 v[64:67], v[188:191], v[72:75], v[80:83]
	v_mfma_f32_16x16x32_bf16 v[16:19], v[200:203], v[72:75], v[16:19]
	v_mfma_f32_16x16x32_bf16 v[44:47], v[180:183], v[84:87], v[44:47]
	v_mfma_f32_16x16x32_bf16 v[60:63], v[188:191], v[84:87], v[60:63]
	v_mfma_f32_16x16x32_bf16 v[32:35], v[200:203], v[84:87], v[32:35]
	s_waitcnt vmcnt(17)
	v_mfma_f32_16x16x32_bf16 v[4:7], v[92:95], v[160:163], v[4:7]
	v_mfma_f32_16x16x32_bf16 v[28:31], v[92:95], v[48:51], v[28:31]
	v_mfma_f32_16x16x32_bf16 v[56:59], v[108:111], v[48:51], v[56:59]
	v_mfma_f32_16x16x32_bf16 v[68:71], v[152:155], v[48:51], v[68:71]
	s_waitcnt vmcnt(16)
	v_mfma_f32_16x16x32_bf16 v[8:11], v[204:207], v[48:51], v[8:11]
	v_mfma_f32_16x16x32_bf16 v[20:23], v[92:95], v[104:107], v[20:23]
	v_mfma_f32_16x16x32_bf16 v[24:27], v[108:111], v[104:107], v[24:27]
	v_mfma_f32_16x16x32_bf16 v[40:43], v[152:155], v[104:107], v[40:43]
	v_mfma_f32_16x16x32_bf16 v[12:15], v[204:207], v[104:107], v[12:15]
	v_mfma_f32_16x16x32_bf16 v[36:39], v[92:95], v[124:127], v[36:39]
	v_mfma_f32_16x16x32_bf16 v[48:51], v[108:111], v[124:127], v[52:55]
	v_mfma_f32_16x16x32_bf16 v[52:55], v[152:155], v[124:127], v[64:67]
	v_mfma_f32_16x16x32_bf16 v[16:19], v[204:207], v[124:127], v[16:19]
	v_mfma_f32_16x16x32_bf16 v[44:47], v[108:111], v[160:163], v[44:47]
	v_mfma_f32_16x16x32_bf16 v[60:63], v[152:155], v[160:163], v[60:63]
	v_mfma_f32_16x16x32_bf16 v[32:35], v[204:207], v[160:163], v[32:35]
	s_waitcnt vmcnt(9)
	v_mfma_f32_16x16x32_bf16 v[4:7], v[96:99], v[164:167], v[4:7]
	v_mfma_f32_16x16x32_bf16 v[28:31], v[96:99], v[88:91], v[28:31]
	v_mfma_f32_16x16x32_bf16 v[56:59], v[116:119], v[88:91], v[56:59]
	v_mfma_f32_16x16x32_bf16 v[64:67], v[156:159], v[88:91], v[68:71]
	s_waitcnt vmcnt(8)
	v_mfma_f32_16x16x32_bf16 v[8:11], v[168:171], v[88:91], v[8:11]
	v_mfma_f32_16x16x32_bf16 v[20:23], v[96:99], v[112:115], v[20:23]
	v_mfma_f32_16x16x32_bf16 v[24:27], v[116:119], v[112:115], v[24:27]
	v_mfma_f32_16x16x32_bf16 v[40:43], v[156:159], v[112:115], v[40:43]
	v_mfma_f32_16x16x32_bf16 v[12:15], v[168:171], v[112:115], v[12:15]
	v_mfma_f32_16x16x32_bf16 v[36:39], v[96:99], v[128:131], v[36:39]
	v_mfma_f32_16x16x32_bf16 v[48:51], v[116:119], v[128:131], v[48:51]
	v_mfma_f32_16x16x32_bf16 v[52:55], v[156:159], v[128:131], v[52:55]
	v_mfma_f32_16x16x32_bf16 v[16:19], v[168:171], v[128:131], v[16:19]
	v_mfma_f32_16x16x32_bf16 v[44:47], v[116:119], v[164:167], v[44:47]
	v_mfma_f32_16x16x32_bf16 v[60:63], v[156:159], v[164:167], v[60:63]
	v_mfma_f32_16x16x32_bf16 v[32:35], v[168:171], v[164:167], v[32:35]
	s_waitcnt vmcnt(1)
	v_mfma_f32_16x16x32_bf16 v[4:7], v[120:123], v[176:179], v[4:7]
	v_mfma_f32_16x16x32_bf16 v[28:31], v[120:123], v[100:103], v[28:31]
	v_mfma_f32_16x16x32_bf16 v[56:59], v[136:139], v[100:103], v[56:59]
	v_mfma_f32_16x16x32_bf16 v[64:67], v[172:175], v[100:103], v[64:67]
	s_waitcnt vmcnt(0)
	v_mfma_f32_16x16x32_bf16 v[8:11], v[184:187], v[100:103], v[8:11]
	v_mfma_f32_16x16x32_bf16 v[20:23], v[120:123], v[132:135], v[20:23]
	v_mfma_f32_16x16x32_bf16 v[24:27], v[136:139], v[132:135], v[24:27]
	v_mfma_f32_16x16x32_bf16 v[40:43], v[172:175], v[132:135], v[40:43]
	v_mfma_f32_16x16x32_bf16 v[12:15], v[184:187], v[132:135], v[12:15]
	v_mfma_f32_16x16x32_bf16 v[36:39], v[120:123], v[144:147], v[36:39]
	v_mfma_f32_16x16x32_bf16 v[48:51], v[136:139], v[144:147], v[48:51]
	v_mfma_f32_16x16x32_bf16 v[52:55], v[172:175], v[144:147], v[52:55]
	v_mfma_f32_16x16x32_bf16 v[16:19], v[184:187], v[144:147], v[16:19]
	v_mfma_f32_16x16x32_bf16 v[44:47], v[136:139], v[176:179], v[44:47]
	v_mfma_f32_16x16x32_bf16 v[60:63], v[172:175], v[176:179], v[60:63]
	v_mfma_f32_16x16x32_bf16 v[32:35], v[184:187], v[176:179], v[32:35]
	v_readlane_b32 s1, v251, 1
	s_and_b32 s1, s1, 0xfffffc0
	s_lshl_b32 s8, s88, 3
	v_or_b32_e32 v1, s1, v1
	s_movk_i32 s1, 0x110
	v_mul_lo_u32 v1, v1, s1
	v_add3_u32 v1, 0, v2, v1
	ds_write_b128 v1, v[28:31]
	ds_write_b128 v1, v[56:59] offset:64
	ds_write_b128 v1, v[64:67] offset:128
	ds_write_b128 v1, v[8:11] offset:192
	ds_write_b128 v1, v[20:23] offset:4352
	ds_write_b128 v1, v[24:27] offset:4416
	ds_write_b128 v1, v[40:43] offset:4480
	ds_write_b128 v1, v[12:15] offset:4544
	ds_write_b128 v1, v[36:39] offset:8704
	ds_write_b128 v1, v[48:51] offset:8768
	ds_write_b128 v1, v[52:55] offset:8832
	ds_write_b128 v1, v[16:19] offset:8896
	ds_write_b128 v1, v[4:7] offset:13056
	ds_write_b128 v1, v[44:47] offset:13120
	ds_write_b128 v1, v[60:63] offset:13184
	ds_write_b128 v1, v[32:35] offset:13248
	v_lshrrev_b32_e32 v1, 3, v198
	v_lshlrev_b32_e32 v4, 3, v0
	v_or_b32_e32 v2, s8, v1
	v_and_b32_e32 v5, 56, v4
	v_lshlrev_b32_e32 v4, 2, v5
	v_mul_lo_u32 v2, v2, s1
	v_add3_u32 v2, 0, v4, v2
	v_add_u32_e32 v4, 0x11000, v2
	v_add_u32_e32 v42, 0x11010, v2
	s_waitcnt lgkmcnt(0)
	s_waitcnt lgkmcnt(0)
	s_barrier
	ds_read_b128 v[6:9], v2
	ds_read_b128 v[10:13], v2 offset:16
	ds_read_b128 v[14:17], v2 offset:17408
	ds_read_b128 v[18:21], v2 offset:17424
	ds_read_b128 v[22:25], v2 offset:34816
	ds_read_b128 v[26:29], v2 offset:34832
	ds_read_b128 v[30:33], v2 offset:52224
	ds_read_b128 v[34:37], v2 offset:52240
	ds_read_b128 v[38:41], v4
	ds_read_b128 v[42:45], v42
	v_add_u32_e32 v4, 0x15400, v2
	v_add_u32_e32 v50, 0x15410, v2
	ds_read_b128 v[46:49], v4
	ds_read_b128 v[50:53], v50
	v_add_u32_e32 v4, 0x19800, v2
	v_add_u32_e32 v58, 0x19810, v2
	ds_read_b128 v[54:57], v4
	ds_read_b128 v[58:61], v58
	v_add_u32_e32 v4, 0x1dc00, v2
	s_add_i32 s8, s8, s0
	v_add_u32_e32 v2, 0x1dc10, v2
	ds_read_b128 v[62:65], v4
	ds_read_b128 v[66:69], v2
	v_or_b32_e32 v4, s8, v1
	v_lshl_or_b32 v1, s10, 6, v5
	v_ashrrev_i32_e32 v5, 31, v4
	v_readlane_b32 s36, v251, 6
	v_lshlrev_b64 v[70:71], 13, v[4:5]
	v_readlane_b32 s38, v251, 8
	v_readlane_b32 s39, v251, 9
	v_lshlrev_b32_e32 v2, 2, v1
	s_brev_b32 s0, 63
	v_lshl_add_u64 v[70:71], s[38:39], 0, v[70:71]
	v_lshl_add_u64 v[74:75], v[70:71], 0, v[2:3]
	s_brev_b32 s8, 63
	s_mov_b32 s1, -1
	v_add_co_u32_e32 v70, vcc, s8, v74
	s_waitcnt lgkmcnt(0)
	s_waitcnt lgkmcnt(0)
	s_nop 0
	v_addc_co_u32_e32 v71, vcc, -1, v75, vcc
	v_lshl_add_u64 v[74:75], v[74:75], 0, s[0:1]
	s_barrier
	global_load_dwordx4 v[70:73], v[70:71], off
	v_pk_add_f32 v[8:9], v[8:9], 0 op_sel_hi:[1,0]
	global_load_dwordx4 v[74:77], v[74:75], off offset:16
	v_pk_add_f32 v[6:7], v[6:7], 0 op_sel_hi:[1,0]
	v_pk_add_f32 v[12:13], v[12:13], 0 op_sel_hi:[1,0]
	v_pk_add_f32 v[10:11], v[10:11], 0 op_sel_hi:[1,0]
	v_pk_add_f32 v[8:9], v[8:9], v[16:17]
	v_pk_add_f32 v[6:7], v[6:7], v[14:15]
	v_pk_add_f32 v[12:13], v[12:13], v[20:21]
	v_pk_add_f32 v[10:11], v[10:11], v[18:19]
	v_pk_add_f32 v[8:9], v[8:9], v[24:25]
	v_pk_add_f32 v[6:7], v[6:7], v[22:23]
	v_pk_add_f32 v[12:13], v[12:13], v[28:29]
	v_pk_add_f32 v[10:11], v[10:11], v[26:27]
	v_pk_add_f32 v[8:9], v[8:9], v[32:33]
	v_pk_add_f32 v[6:7], v[6:7], v[30:31]
	v_pk_add_f32 v[12:13], v[12:13], v[36:37]
	v_pk_add_f32 v[10:11], v[10:11], v[34:35]
	v_pk_add_f32 v[8:9], v[8:9], v[40:41]
	v_pk_add_f32 v[6:7], v[6:7], v[38:39]
	v_pk_add_f32 v[12:13], v[12:13], v[44:45]
	v_pk_add_f32 v[10:11], v[10:11], v[42:43]
	v_pk_add_f32 v[8:9], v[8:9], v[48:49]
	v_pk_add_f32 v[6:7], v[6:7], v[46:47]
	v_pk_add_f32 v[12:13], v[12:13], v[52:53]
	v_pk_add_f32 v[10:11], v[10:11], v[50:51]
	v_pk_add_f32 v[8:9], v[8:9], v[56:57]
	v_pk_add_f32 v[6:7], v[6:7], v[54:55]
	v_pk_add_f32 v[12:13], v[12:13], v[60:61]
	v_pk_add_f32 v[10:11], v[10:11], v[58:59]
	v_pk_add_f32 v[8:9], v[8:9], v[64:65]
	v_pk_add_f32 v[6:7], v[6:7], v[62:63]
	v_pk_add_f32 v[12:13], v[12:13], v[68:69]
	v_pk_add_f32 v[10:11], v[10:11], v[66:67]
	v_lshlrev_b64 v[18:19], 12, v[4:5]
	v_lshl_add_u64 v[18:19], s[4:5], 0, v[18:19]
	v_lshlrev_b32_e32 v2, 1, v1
	v_lshl_add_u64 v[2:3], v[18:19], 0, v[2:3]
	v_readlane_b32 s37, v251, 7
	v_readlane_b32 s40, v251, 10
	v_readlane_b32 s41, v251, 11
	v_readlane_b32 s42, v251, 12
	v_readlane_b32 s43, v251, 13
	v_readlane_b32 s44, v251, 14
	v_readlane_b32 s45, v251, 15
	v_readlane_b32 s46, v251, 16
	v_readlane_b32 s47, v251, 17
	v_readlane_b32 s48, v251, 18
	v_readlane_b32 s49, v251, 19
	v_readlane_b32 s50, v251, 20
	v_readlane_b32 s51, v251, 21
	s_waitcnt vmcnt(1)
	v_pk_add_f32 v[14:15], v[8:9], v[72:73]
	v_pk_add_f32 v[16:17], v[6:7], v[70:71]
	s_waitcnt vmcnt(0)
	v_pk_add_f32 v[12:13], v[12:13], v[76:77]
	v_pk_add_f32 v[10:11], v[10:11], v[74:75]
	v_cvt_pk_bf16_f32 v6, v16, v17
	v_cvt_pk_bf16_f32 v7, v14, v15
	v_cvt_pk_bf16_f32 v8, v10, v11
	v_cvt_pk_bf16_f32 v9, v12, v13
	global_store_dwordx4 v[2:3], v[6:9], off
	v_mul_f32_e32 v1, v17, v17
	v_mul_f32_e32 v2, v15, v15
	v_fmac_f32_e32 v1, v16, v16
	v_fmac_f32_e32 v2, v14, v14
	v_add_f32_e32 v1, v1, v2
	v_mul_f32_e32 v2, v11, v11
	v_fmac_f32_e32 v2, v10, v10
	v_add_f32_e32 v1, v1, v2
	v_mul_f32_e32 v2, v13, v13
	v_fmac_f32_e32 v2, v12, v12
	v_add_f32_e32 v1, v2, v1
	v_and_b32_e32 v3, 7, v0
	v_cmp_eq_u32_e32 vcc, 0, v3
	v_add_f32_dpp v1, v1, v1 quad_perm:[1,0,3,2] row_mask:0xf bank_mask:0xf bound_ctrl:1
	s_nop 1
	v_add_f32_dpp v1, v1, v1 quad_perm:[2,3,0,1] row_mask:0xf bank_mask:0xf bound_ctrl:1
	s_nop 1
	v_mov_b32_dpp v2, v1 row_half_mirror row_mask:0xf bank_mask:0xf bound_ctrl:1
	s_and_saveexec_b64 s[0:1], vcc
	s_cbranch_execz .LBB0_2459
	v_lshlrev_b64 v[4:5], 7, v[4:5]
	v_lshl_add_u64 v[4:5], s[2:3], 0, v[4:5]
	s_lshl_b32 s8, s10, 2
	s_mov_b32 s9, 0
	v_lshl_add_u64 v[4:5], v[4:5], 0, s[8:9]
	v_add_f32_e32 v1, v1, v2
	global_store_dword v[4:5], v1, off

	.amdhsa_kernel _Z10hybrid_fwdILi3EEv4Args
		.amdhsa_group_segment_fixed_size 0
		.amdhsa_private_segment_fixed_size 0
		.amdhsa_kernarg_size 520
		.amdhsa_user_sgpr_count 2
		.amdhsa_user_sgpr_dispatch_ptr 0
		.amdhsa_user_sgpr_queue_ptr 0
		.amdhsa_user_sgpr_kernarg_segment_ptr 1
		.amdhsa_user_sgpr_dispatch_id 0
		.amdhsa_user_sgpr_kernarg_preload_length 0
		.amdhsa_user_sgpr_kernarg_preload_offset 0
		.amdhsa_user_sgpr_private_segment_size 0
		.amdhsa_uses_dynamic_stack 0
		.amdhsa_enable_private_segment 0
		.amdhsa_system_sgpr_workgroup_id_x 1
		.amdhsa_system_sgpr_workgroup_id_y 0
		.amdhsa_system_sgpr_workgroup_id_z 0
		.amdhsa_system_sgpr_workgroup_info 0
		.amdhsa_system_vgpr_workitem_id 0
		.amdhsa_next_free_vgpr 256
		.amdhsa_next_free_sgpr 98
		.amdhsa_accum_offset 256
		.amdhsa_reserve_vcc 1
		.amdhsa_float_round_mode_32 0
		.amdhsa_float_round_mode_16_64 0
		.amdhsa_float_denorm_mode_32 3
		.amdhsa_float_denorm_mode_16_64 3
		.amdhsa_dx10_clamp 1
		.amdhsa_ieee_mode 1
		.amdhsa_fp16_overflow 0
		.amdhsa_tg_split 0
		.amdhsa_exception_fp_ieee_invalid_op 0
		.amdhsa_exception_fp_denorm_src 0
		.amdhsa_exception_fp_ieee_div_zero 0
		.amdhsa_exception_fp_ieee_overflow 0
		.amdhsa_exception_fp_ieee_underflow 0
		.amdhsa_exception_fp_ieee_inexact 0
		.amdhsa_exception_int_div_zero 0
	.end_amdhsa_kernel

amdhsa.kernels:
  - .agpr_count:     0
    .args:
      - .offset:         0
        .size:           264
        .value_kind:     by_value
      - .offset:         264
        .size:           4
        .value_kind:     hidden_block_count_x
      - .offset:         268
        .size:           4
        .value_kind:     hidden_block_count_y
      - .offset:         272
        .size:           4
        .value_kind:     hidden_block_count_z
      - .offset:         276
        .size:           2
        .value_kind:     hidden_group_size_x
      - .offset:         278
        .size:           2
        .value_kind:     hidden_group_size_y
      - .offset:         280
        .size:           2
        .value_kind:     hidden_group_size_z
      - .offset:         282
        .size:           2
        .value_kind:     hidden_remainder_x
      - .offset:         284
        .size:           2
        .value_kind:     hidden_remainder_y
      - .offset:         286
        .size:           2
        .value_kind:     hidden_remainder_z
      - .offset:         304
        .size:           8
        .value_kind:     hidden_global_offset_x
      - .offset:         312
        .size:           8
        .value_kind:     hidden_global_offset_y
      - .offset:         320
        .size:           8
        .value_kind:     hidden_global_offset_z
      - .offset:         328
        .size:           2
        .value_kind:     hidden_grid_dims
      - .offset:         384
        .size:           4
        .value_kind:     hidden_dynamic_lds_size
    .group_segment_fixed_size: 0
    .kernarg_segment_align: 8
    .kernarg_segment_size: 520
    .language:       OpenCL C
    .language_version:
      - 2
      - 0
    .max_flat_workgroup_size: 512
    .name:           _Z10hybrid_fwdILi3EEv4Args
    .private_segment_fixed_size: 0
    .sgpr_count:     104
    .sgpr_spill_count: 426
    .symbol:         _Z10hybrid_fwdILi3EEv4Args.kd
    .uniform_work_group_size: 1
    .uses_dynamic_stack: false
    .vgpr_count:     256
    .vgpr_spill_count: 0
    .wavefront_size: 64
